# v40 plus counted wait (vmcnt 5) instead of hipcc's vmcnt(0) in the accumulator zero-init of the in_c / out-proj / up / down unit-loop headers (the wait no longer drains the just-issued epilogue prefet
# speedup vs baseline: 1.0021x; 1.0021x over previous
;     __device__ __forceinline__ size_t aoff(const Unit& u) const { return (size_t)u.pm * bm * lda * 2; }
;     __device__ __forceinline__ size_t boff(const Unit& u) const { return (size_t)u.pn * BM * ldb * 2; }
;     __device__ __forceinline__ size_t aoff(const Unit& u) const { return ((size_t)u.pm * BM * lda + (size_t)u.pn * akoff) * 2; }
;     __device__ __forceinline__ size_t boff(const Unit& u) const { return (size_t)u.pn * BM * ldb * 2; }
;     __device__ __forceinline__ size_t aoff(const Unit& u) const { return ((size_t)u.pm * BM * lda + (size_t)(u.pn >> 1) * akoff) * 2; }
;     __device__ __forceinline__ size_t boff(const Unit& u) const { return (size_t)u.pn * BM * ldb * 2; }
;     ...
;         const bool has_next = S.next(ui + 1, nxt);
;         const char* nA = has_next ? (const char*)g.A + S.aoff(nxt) : cA; const char* nB = has_next ? (const char*)g.Bt + S.boff(nxt) : cB;
;         if constexpr (Epi::PRE) E.pre(lds, cur, wid);
;         for (int t = 0; t < nt; t += 2) {
;             const bool last = (t == nt - 2);
;             const char* a1 = cA + (size_t)(t + 1) * kstep;
;             const char* a2 = last ? nA : cA + (size_t)(t + 2) * kstep; const char* b2 = last ? nB : cB + (size_t)(t + 2) * kstep;
;             const char* a3 = a2 + kstep; const char* b3 = b2 + kstep;
;     ...
; #pragma unroll
;         for (int a = 0; a < 2; ++a)
; #pragma unroll
;             for (int b = 0; b < 2; ++b)
; #pragma unroll
;                 for (int m = 0; m < NM; ++m)
; #pragma unroll
;                     for (int n = 0; n < 2; ++n) acc[a][b][m][n] = (f32x4){0.f, 0.f, 0.f, 0.f};
;         cur = nxt; cA = nA; cB = nB; ++ui; cur.par = ui & 1;
.LBB0_199:
	s_ashr_i32 s23, s22, 31
	s_lshl_b64 s[2:3], s[22:23], 20
	s_add_u32 s24, s33, s2
	s_addc_u32 s25, s36, s3
	s_and_b64 s[2:3], s[4:5], exec
	s_cselect_b32 s2, s25, s29
	s_cselect_b32 s3, s24, s28
	s_ashr_i32 s21, s20, 31
	s_lshl_b64 s[26:27], s[20:21], 20
	s_add_u32 s26, s37, s26
	s_addc_u32 s27, s38, s27
	s_and_b64 s[34:35], s[4:5], exec
	s_cselect_b32 s9, s27, s31
	s_cselect_b32 s21, s26, s30
	s_add_u32 s28, s28, 0x80080
	s_addc_u32 s29, s29, 0
	s_add_u32 s23, s30, 0x100
	v_mov_b32_e32 v2, 0
	s_addc_u32 s54, s31, 0
	s_mov_b32 s56, -2
	v_mov_b32_e32 v3, v2
	v_mov_b32_e32 v4, v2
	v_mov_b32_e32 v5, v2
	v_mov_b32_e32 v6, v2
	v_mov_b32_e32 v7, v2
	v_mov_b32_e32 v8, v2
	v_mov_b32_e32 v9, v2
	v_mov_b32_e32 v18, v2
	v_mov_b32_e32 v19, v2
	v_mov_b32_e32 v20, v2
	v_mov_b32_e32 v21, v2
	v_mov_b32_e32 v22, v2
	v_mov_b32_e32 v23, v2
	v_mov_b32_e32 v24, v2
	v_mov_b32_e32 v25, v2
	v_mov_b32_e32 v50, v2
	v_mov_b32_e32 v51, v2
	v_mov_b32_e32 v52, v2
	v_mov_b32_e32 v53, v2
	v_mov_b32_e32 v54, v2
	v_mov_b32_e32 v55, v2
	v_mov_b32_e32 v56, v2
	v_mov_b32_e32 v57, v2
	v_mov_b32_e32 v66, v2
	s_waitcnt vmcnt(5)
	v_mov_b32_e32 v67, v2
	v_mov_b32_e32 v68, v2
	v_mov_b32_e32 v69, v2
	v_mov_b32_e32 v70, v2
	v_mov_b32_e32 v71, v2
	v_mov_b32_e32 v72, v2
	v_mov_b32_e32 v73, v2
	v_mov_b32_e32 v10, v2
	v_mov_b32_e32 v11, v2
	v_mov_b32_e32 v12, v2
	v_mov_b32_e32 v13, v2
	v_mov_b32_e32 v14, v2
	v_mov_b32_e32 v15, v2
	v_mov_b32_e32 v16, v2
	v_mov_b32_e32 v17, v2
	v_mov_b32_e32 v34, v2
	v_mov_b32_e32 v35, v2
	v_mov_b32_e32 v36, v2
	v_mov_b32_e32 v37, v2
	v_mov_b32_e32 v38, v2
	v_mov_b32_e32 v39, v2
	v_mov_b32_e32 v40, v2
	v_mov_b32_e32 v41, v2
	v_mov_b32_e32 v58, v2
	v_mov_b32_e32 v59, v2
	v_mov_b32_e32 v60, v2
	v_mov_b32_e32 v61, v2
	v_mov_b32_e32 v62, v2
	v_mov_b32_e32 v63, v2
	v_mov_b32_e32 v64, v2
	v_mov_b32_e32 v65, v2
	v_mov_b32_e32 v74, v2
	v_mov_b32_e32 v75, v2
	v_mov_b32_e32 v76, v2
	v_mov_b32_e32 v77, v2
	v_mov_b32_e32 v78, v2
	v_mov_b32_e32 v79, v2
	v_mov_b32_e32 v80, v2
	v_mov_b32_e32 v81, v2
	v_mov_b32_e32 v82, v2
	v_mov_b32_e32 v83, v2
	v_mov_b32_e32 v84, v2
	v_mov_b32_e32 v85, v2
	v_mov_b32_e32 v86, v2
	v_mov_b32_e32 v87, v2
	v_mov_b32_e32 v88, v2
	v_mov_b32_e32 v89, v2
	v_mov_b32_e32 v98, v2
	v_mov_b32_e32 v99, v2
	v_mov_b32_e32 v100, v2
	v_mov_b32_e32 v101, v2
	v_mov_b32_e32 v102, v2
	v_mov_b32_e32 v103, v2
	v_mov_b32_e32 v104, v2
	v_mov_b32_e32 v105, v2
	v_mov_b32_e32 v114, v2
	v_mov_b32_e32 v115, v2
	v_mov_b32_e32 v116, v2
	v_mov_b32_e32 v117, v2
	v_mov_b32_e32 v118, v2
	v_mov_b32_e32 v119, v2
	v_mov_b32_e32 v120, v2
	v_mov_b32_e32 v121, v2
	v_mov_b32_e32 v130, v2
	v_mov_b32_e32 v131, v2
	v_mov_b32_e32 v132, v2
	v_mov_b32_e32 v133, v2
	v_mov_b32_e32 v134, v2
	v_mov_b32_e32 v135, v2
	v_mov_b32_e32 v136, v2
	v_mov_b32_e32 v137, v2
	v_mov_b32_e32 v90, v2
	v_mov_b32_e32 v91, v2
	v_mov_b32_e32 v92, v2
	v_mov_b32_e32 v93, v2
	v_mov_b32_e32 v94, v2
	v_mov_b32_e32 v95, v2
	v_mov_b32_e32 v96, v2
	v_mov_b32_e32 v97, v2
	v_mov_b32_e32 v106, v2
	v_mov_b32_e32 v107, v2
	v_mov_b32_e32 v108, v2
	v_mov_b32_e32 v109, v2
	v_mov_b32_e32 v110, v2
	v_mov_b32_e32 v111, v2
	v_mov_b32_e32 v112, v2
	v_mov_b32_e32 v113, v2
	v_mov_b32_e32 v122, v2
	v_mov_b32_e32 v123, v2
	v_mov_b32_e32 v124, v2
	v_mov_b32_e32 v125, v2
	v_mov_b32_e32 v126, v2
	v_mov_b32_e32 v127, v2
	v_mov_b32_e32 v128, v2
	v_mov_b32_e32 v129, v2
	v_mov_b32_e32 v138, v2
	v_mov_b32_e32 v139, v2
	v_mov_b32_e32 v140, v2
	v_mov_b32_e32 v141, v2
	v_mov_b32_e32 v142, v2
	v_mov_b32_e32 v143, v2
	v_mov_b32_e32 v144, v2
	v_mov_b32_e32 v145, v2

;     __device__ __forceinline__ size_t aoff(const Unit& u) const { return (size_t)u.pm * bm * lda * 2; }
;     __device__ __forceinline__ size_t boff(const Unit& u) const { return (size_t)u.pn * BM * ldb * 2; }
;     __device__ __forceinline__ size_t aoff(const Unit& u) const { return ((size_t)u.pm * BM * lda + (size_t)u.pn * akoff) * 2; }
;     __device__ __forceinline__ size_t boff(const Unit& u) const { return (size_t)u.pn * BM * ldb * 2; }
;     __device__ __forceinline__ size_t aoff(const Unit& u) const { return ((size_t)u.pm * BM * lda + (size_t)(u.pn >> 1) * akoff) * 2; }
;     __device__ __forceinline__ size_t boff(const Unit& u) const { return (size_t)u.pn * BM * ldb * 2; }
;     ...
;         const bool has_next = S.next(ui + 1, nxt);
;         const char* nA = has_next ? (const char*)g.A + S.aoff(nxt) : cA; const char* nB = has_next ? (const char*)g.Bt + S.boff(nxt) : cB;
;         if constexpr (Epi::PRE) E.pre(lds, cur, wid);
;         for (int t = 0; t < nt; t += 2) {
;             const bool last = (t == nt - 2);
;             const char* a1 = cA + (size_t)(t + 1) * kstep;
;             const char* a2 = last ? nA : cA + (size_t)(t + 2) * kstep; const char* b2 = last ? nB : cB + (size_t)(t + 2) * kstep;
;             const char* a3 = a2 + kstep; const char* b3 = b2 + kstep;
;     ...
; #pragma unroll
;         for (int a = 0; a < 2; ++a)
; #pragma unroll
;             for (int b = 0; b < 2; ++b)
; #pragma unroll
;                 for (int m = 0; m < NM; ++m)
; #pragma unroll
;                     for (int n = 0; n < 2; ++n) acc[a][b][m][n] = (f32x4){0.f, 0.f, 0.f, 0.f};
;         cur = nxt; cA = nA; cB = nB; ++ui; cur.par = ui & 1;
.LBB0_1649:
	s_ashr_i32 s15, s14, 31
	s_lshl_b64 s[2:3], s[14:15], 20
	s_add_u32 s18, s5, s2
	s_addc_u32 s19, s26, s3
	s_and_b64 s[2:3], s[8:9], exec
	s_cselect_b32 s2, s19, s23
	s_cselect_b32 s3, s18, s22
	s_add_u32 s8, s24, 0x60080
	s_addc_u32 s9, s25, 0
	s_add_u32 s15, s22, 0x100
	v_mov_b32_e32 v2, 0
	s_addc_u32 s58, s23, 0
	s_mov_b32 s59, -2
	v_mov_b32_e32 v3, v2
	v_mov_b32_e32 v4, v2
	v_mov_b32_e32 v5, v2
	v_mov_b32_e32 v6, v2
	v_mov_b32_e32 v7, v2
	v_mov_b32_e32 v8, v2
	v_mov_b32_e32 v9, v2
	v_mov_b32_e32 v18, v2
	v_mov_b32_e32 v19, v2
	v_mov_b32_e32 v20, v2
	v_mov_b32_e32 v21, v2
	v_mov_b32_e32 v22, v2
	v_mov_b32_e32 v23, v2
	v_mov_b32_e32 v24, v2
	v_mov_b32_e32 v25, v2
	s_waitcnt vmcnt(5)
	v_mov_b32_e32 v34, v2
	v_mov_b32_e32 v35, v2
	v_mov_b32_e32 v36, v2
	v_mov_b32_e32 v37, v2
	v_mov_b32_e32 v38, v2
	v_mov_b32_e32 v39, v2
	v_mov_b32_e32 v40, v2
	v_mov_b32_e32 v41, v2
	v_mov_b32_e32 v10, v2
	v_mov_b32_e32 v11, v2
	v_mov_b32_e32 v12, v2
	v_mov_b32_e32 v13, v2
	v_mov_b32_e32 v14, v2
	v_mov_b32_e32 v15, v2
	v_mov_b32_e32 v16, v2
	v_mov_b32_e32 v17, v2
	v_mov_b32_e32 v26, v2
	v_mov_b32_e32 v27, v2
	v_mov_b32_e32 v28, v2
	v_mov_b32_e32 v29, v2
	v_mov_b32_e32 v30, v2
	v_mov_b32_e32 v31, v2
	v_mov_b32_e32 v32, v2
	v_mov_b32_e32 v33, v2
	v_mov_b32_e32 v42, v2
	v_mov_b32_e32 v43, v2
	v_mov_b32_e32 v44, v2
	v_mov_b32_e32 v45, v2
	v_mov_b32_e32 v46, v2
	v_mov_b32_e32 v47, v2
	v_mov_b32_e32 v48, v2
	v_mov_b32_e32 v49, v2
	v_mov_b32_e32 v50, v2
	v_mov_b32_e32 v51, v2
	v_mov_b32_e32 v52, v2
	v_mov_b32_e32 v53, v2
	v_mov_b32_e32 v54, v2
	v_mov_b32_e32 v55, v2
	v_mov_b32_e32 v56, v2
	v_mov_b32_e32 v57, v2
	v_mov_b32_e32 v66, v2
	v_mov_b32_e32 v67, v2
	v_mov_b32_e32 v68, v2
	v_mov_b32_e32 v69, v2
	v_mov_b32_e32 v70, v2
	v_mov_b32_e32 v71, v2
	v_mov_b32_e32 v72, v2
	v_mov_b32_e32 v73, v2
	v_mov_b32_e32 v82, v2
	v_mov_b32_e32 v83, v2
	v_mov_b32_e32 v84, v2
	v_mov_b32_e32 v85, v2
	v_mov_b32_e32 v86, v2
	v_mov_b32_e32 v87, v2
	v_mov_b32_e32 v88, v2
	v_mov_b32_e32 v89, v2
	v_mov_b32_e32 v58, v2
	v_mov_b32_e32 v59, v2
	v_mov_b32_e32 v60, v2
	v_mov_b32_e32 v61, v2
	v_mov_b32_e32 v62, v2
	v_mov_b32_e32 v63, v2
	v_mov_b32_e32 v64, v2
	v_mov_b32_e32 v65, v2
	v_mov_b32_e32 v74, v2
	v_mov_b32_e32 v75, v2
	v_mov_b32_e32 v76, v2
	v_mov_b32_e32 v77, v2
	v_mov_b32_e32 v78, v2
	v_mov_b32_e32 v79, v2
	v_mov_b32_e32 v80, v2
	v_mov_b32_e32 v81, v2
	v_mov_b32_e32 v106, v2
	v_mov_b32_e32 v107, v2
	v_mov_b32_e32 v108, v2
	v_mov_b32_e32 v109, v2
	v_mov_b32_e32 v110, v2
	v_mov_b32_e32 v111, v2
	v_mov_b32_e32 v112, v2
	v_mov_b32_e32 v113, v2

;     __device__ __forceinline__ size_t aoff(const Unit& u) const { return (size_t)u.pm * bm * lda * 2; }
;     __device__ __forceinline__ size_t boff(const Unit& u) const { return (size_t)u.pn * BM * ldb * 2; }
;     __device__ __forceinline__ size_t aoff(const Unit& u) const { return ((size_t)u.pm * BM * lda + (size_t)u.pn * akoff) * 2; }
;     __device__ __forceinline__ size_t boff(const Unit& u) const { return (size_t)u.pn * BM * ldb * 2; }
;     __device__ __forceinline__ size_t aoff(const Unit& u) const { return ((size_t)u.pm * BM * lda + (size_t)(u.pn >> 1) * akoff) * 2; }
;     __device__ __forceinline__ size_t boff(const Unit& u) const { return (size_t)u.pn * BM * ldb * 2; }
;     ...
;         const bool has_next = S.next(ui + 1, nxt);
;         const char* nA = has_next ? (const char*)g.A + S.aoff(nxt) : cA; const char* nB = has_next ? (const char*)g.Bt + S.boff(nxt) : cB;
;         if constexpr (Epi::PRE) E.pre(lds, cur, wid);
;         for (int t = 0; t < nt; t += 2) {
;             const bool last = (t == nt - 2);
;             const char* a1 = cA + (size_t)(t + 1) * kstep;
;             const char* a2 = last ? nA : cA + (size_t)(t + 2) * kstep; const char* b2 = last ? nB : cB + (size_t)(t + 2) * kstep;
;             const char* a3 = a2 + kstep; const char* b3 = b2 + kstep;
;     ...
; #pragma unroll
;         for (int a = 0; a < 2; ++a)
; #pragma unroll
;             for (int b = 0; b < 2; ++b)
; #pragma unroll
;                 for (int m = 0; m < NM; ++m)
; #pragma unroll
;                     for (int n = 0; n < 2; ++n) acc[a][b][m][n] = (f32x4){0.f, 0.f, 0.f, 0.f};
;         cur = nxt; cA = nA; cB = nB; ++ui; cur.par = ui & 1;
.LBB0_1782:
	s_ashr_i32 s41, s40, 31
	s_lshl_b64 s[2:3], s[40:41], 20
	s_add_u32 s42, s33, s2
	s_addc_u32 s43, s48, s3
	s_and_b64 s[2:3], s[6:7], exec
	s_cselect_b32 s2, s43, s13
	s_cselect_b32 s3, s42, s12
	s_ashr_i32 s37, s36, 31
	s_lshl_b64 s[44:45], s[36:37], 20
	s_add_u32 s44, s60, s44
	s_addc_u32 s45, s63, s45
	s_and_b64 s[46:47], s[6:7], exec
	s_cselect_b32 s9, s45, s15
	s_cselect_b32 s11, s44, s14
	s_add_u32 s12, s12, 0x80080
	s_addc_u32 s13, s13, 0
	s_add_u32 s37, s14, 0x100
	v_mov_b32_e32 v50, 0
	s_addc_u32 s41, s15, 0
	s_mov_b32 vcc_lo, -2
	v_mov_b32_e32 v51, v50
	v_mov_b32_e32 v52, v50
	v_mov_b32_e32 v53, v50
	s_waitcnt vmcnt(5)
	v_mov_b32_e32 v74, v50
	v_mov_b32_e32 v75, v50
	v_mov_b32_e32 v76, v50
	v_mov_b32_e32 v77, v50
	v_mov_b32_e32 v2, v50
	v_mov_b32_e32 v3, v50
	v_mov_b32_e32 v4, v50
	v_mov_b32_e32 v5, v50
	v_mov_b32_e32 v26, v50
	v_mov_b32_e32 v27, v50
	v_mov_b32_e32 v28, v50
	v_mov_b32_e32 v29, v50
	v_mov_b32_e32 v6, v50
	v_mov_b32_e32 v7, v50
	v_mov_b32_e32 v8, v50
	v_mov_b32_e32 v9, v50
	v_mov_b32_e32 v30, v50
	v_mov_b32_e32 v31, v50
	v_mov_b32_e32 v32, v50
	v_mov_b32_e32 v33, v50
	v_mov_b32_e32 v10, v50
	v_mov_b32_e32 v11, v50
	v_mov_b32_e32 v12, v50
	v_mov_b32_e32 v13, v50
	v_mov_b32_e32 v34, v50
	v_mov_b32_e32 v35, v50
	v_mov_b32_e32 v36, v50
	v_mov_b32_e32 v37, v50
	v_mov_b32_e32 v54, v50
	v_mov_b32_e32 v55, v50
	v_mov_b32_e32 v56, v50
	v_mov_b32_e32 v57, v50
	v_mov_b32_e32 v78, v50
	v_mov_b32_e32 v79, v50
	v_mov_b32_e32 v80, v50
	v_mov_b32_e32 v81, v50
	v_mov_b32_e32 v14, v50
	v_mov_b32_e32 v15, v50
	v_mov_b32_e32 v16, v50
	v_mov_b32_e32 v17, v50
	v_mov_b32_e32 v38, v50
	v_mov_b32_e32 v39, v50
	v_mov_b32_e32 v40, v50
	v_mov_b32_e32 v41, v50
	v_mov_b32_e32 v18, v50
	v_mov_b32_e32 v19, v50
	v_mov_b32_e32 v20, v50
	v_mov_b32_e32 v21, v50
	v_mov_b32_e32 v42, v50
	v_mov_b32_e32 v43, v50
	v_mov_b32_e32 v44, v50
	v_mov_b32_e32 v45, v50
	v_mov_b32_e32 v22, v50
	v_mov_b32_e32 v23, v50
	v_mov_b32_e32 v24, v50
	v_mov_b32_e32 v25, v50
	v_mov_b32_e32 v46, v50
	v_mov_b32_e32 v47, v50
	v_mov_b32_e32 v48, v50
	v_mov_b32_e32 v49, v50
	v_mov_b32_e32 v82, v50
	v_mov_b32_e32 v83, v50
	v_mov_b32_e32 v84, v50
	v_mov_b32_e32 v85, v50
	v_mov_b32_e32 v114, v50
	v_mov_b32_e32 v115, v50
	v_mov_b32_e32 v116, v50
	v_mov_b32_e32 v117, v50
	v_mov_b32_e32 v58, v50
	v_mov_b32_e32 v59, v50
	v_mov_b32_e32 v60, v50
	v_mov_b32_e32 v61, v50
	v_mov_b32_e32 v98, v50
	v_mov_b32_e32 v99, v50
	v_mov_b32_e32 v100, v50
	v_mov_b32_e32 v101, v50
	v_mov_b32_e32 v62, v50
	v_mov_b32_e32 v63, v50
	v_mov_b32_e32 v64, v50
	v_mov_b32_e32 v65, v50
	v_mov_b32_e32 v102, v50
	v_mov_b32_e32 v103, v50
	v_mov_b32_e32 v104, v50
	v_mov_b32_e32 v105, v50
	v_mov_b32_e32 v90, v50
	v_mov_b32_e32 v91, v50
	v_mov_b32_e32 v92, v50
	v_mov_b32_e32 v93, v50
	v_mov_b32_e32 v122, v50
	v_mov_b32_e32 v123, v50
	v_mov_b32_e32 v124, v50
	v_mov_b32_e32 v125, v50
	v_mov_b32_e32 v86, v50
	v_mov_b32_e32 v87, v50
	v_mov_b32_e32 v88, v50
	v_mov_b32_e32 v89, v50
	v_mov_b32_e32 v118, v50
	v_mov_b32_e32 v119, v50
	v_mov_b32_e32 v120, v50
	v_mov_b32_e32 v121, v50
	v_mov_b32_e32 v66, v50
	v_mov_b32_e32 v67, v50
	v_mov_b32_e32 v68, v50
	v_mov_b32_e32 v69, v50
	v_mov_b32_e32 v106, v50
	v_mov_b32_e32 v107, v50
	v_mov_b32_e32 v108, v50
	v_mov_b32_e32 v109, v50
	v_mov_b32_e32 v70, v50
	v_mov_b32_e32 v71, v50
	v_mov_b32_e32 v72, v50
	v_mov_b32_e32 v73, v50
	v_mov_b32_e32 v110, v50
	v_mov_b32_e32 v111, v50
	v_mov_b32_e32 v112, v50
	v_mov_b32_e32 v113, v50
	v_mov_b32_e32 v94, v50
	v_mov_b32_e32 v95, v50
	v_mov_b32_e32 v96, v50
	v_mov_b32_e32 v97, v50
	v_mov_b32_e32 v126, v50
	v_mov_b32_e32 v127, v50
	v_mov_b32_e32 v128, v50
	v_mov_b32_e32 v129, v50

;     ...
;             const char* a1 = cA + (size_t)(t + 1) * kstep;
;             const char* a2 = last ? nA : cA + (size_t)(t + 2) * kstep; const char* b2 = last ? nB : cB + (size_t)(t + 2) * kstep;
;             const char* a3 = a2 + kstep; const char* b3 = b2 + kstep;
;     ...
; #pragma unroll
;         for (int a = 0; a < 2; ++a)
; #pragma unroll
;             for (int b = 0; b < 2; ++b)
; #pragma unroll
;                 for (int m = 0; m < NM; ++m)
; #pragma unroll
;                     for (int n = 0; n < 2; ++n) acc[a][b][m][n] = (f32x4){0.f, 0.f, 0.f, 0.f};
;         cur = nxt; cA = nA; cB = nB; ++ui; cur.par = ui & 1;
.LBB0_2157:
	s_add_u32 s2, s16, 0x100
	v_mov_b32_e32 v2, 0
	s_addc_u32 s3, s17, 0
	s_mov_b32 s60, -2
	v_mov_b32_e32 v3, v2
	v_mov_b32_e32 v4, v2
	v_mov_b32_e32 v5, v2
	v_mov_b32_e32 v6, v2
	v_mov_b32_e32 v7, v2
	v_mov_b32_e32 v8, v2
	v_mov_b32_e32 v9, v2
	v_mov_b32_e32 v18, v2
	v_mov_b32_e32 v19, v2
	v_mov_b32_e32 v20, v2
	v_mov_b32_e32 v21, v2
	v_mov_b32_e32 v22, v2
	v_mov_b32_e32 v23, v2
	v_mov_b32_e32 v24, v2
	v_mov_b32_e32 v25, v2
	s_waitcnt vmcnt(5)
	v_mov_b32_e32 v34, v2
	v_mov_b32_e32 v35, v2
	v_mov_b32_e32 v36, v2
	v_mov_b32_e32 v37, v2
	v_mov_b32_e32 v38, v2
	v_mov_b32_e32 v39, v2
	v_mov_b32_e32 v40, v2
	v_mov_b32_e32 v41, v2
	v_mov_b32_e32 v10, v2
	v_mov_b32_e32 v11, v2
	v_mov_b32_e32 v12, v2
	v_mov_b32_e32 v13, v2
	v_mov_b32_e32 v14, v2
	v_mov_b32_e32 v15, v2
	v_mov_b32_e32 v16, v2
	v_mov_b32_e32 v17, v2
	v_mov_b32_e32 v26, v2
	v_mov_b32_e32 v27, v2
	v_mov_b32_e32 v28, v2
	v_mov_b32_e32 v29, v2
	v_mov_b32_e32 v30, v2
	v_mov_b32_e32 v31, v2
	v_mov_b32_e32 v32, v2
	v_mov_b32_e32 v33, v2
	v_mov_b32_e32 v42, v2
	v_mov_b32_e32 v43, v2
	v_mov_b32_e32 v44, v2
	v_mov_b32_e32 v45, v2
	v_mov_b32_e32 v46, v2
	v_mov_b32_e32 v47, v2
	v_mov_b32_e32 v48, v2
	v_mov_b32_e32 v49, v2
	v_mov_b32_e32 v50, v2
	v_mov_b32_e32 v51, v2
	v_mov_b32_e32 v52, v2
	v_mov_b32_e32 v53, v2
	v_mov_b32_e32 v54, v2
	v_mov_b32_e32 v55, v2
	v_mov_b32_e32 v56, v2
	v_mov_b32_e32 v57, v2
	v_mov_b32_e32 v66, v2
	v_mov_b32_e32 v67, v2
	v_mov_b32_e32 v68, v2
	v_mov_b32_e32 v69, v2
	v_mov_b32_e32 v70, v2
	v_mov_b32_e32 v71, v2
	v_mov_b32_e32 v72, v2
	v_mov_b32_e32 v73, v2
	v_mov_b32_e32 v82, v2
	v_mov_b32_e32 v83, v2
	v_mov_b32_e32 v84, v2
	v_mov_b32_e32 v85, v2
	v_mov_b32_e32 v86, v2
	v_mov_b32_e32 v87, v2
	v_mov_b32_e32 v88, v2
	v_mov_b32_e32 v89, v2
	v_mov_b32_e32 v58, v2
	v_mov_b32_e32 v59, v2
	v_mov_b32_e32 v60, v2
	v_mov_b32_e32 v61, v2
	v_mov_b32_e32 v62, v2
	v_mov_b32_e32 v63, v2
	v_mov_b32_e32 v64, v2
	v_mov_b32_e32 v65, v2
	v_mov_b32_e32 v74, v2
	v_mov_b32_e32 v75, v2
	v_mov_b32_e32 v76, v2
	v_mov_b32_e32 v77, v2
	v_mov_b32_e32 v78, v2
	v_mov_b32_e32 v79, v2
	v_mov_b32_e32 v80, v2
	v_mov_b32_e32 v81, v2
	v_mov_b32_e32 v106, v2
	v_mov_b32_e32 v107, v2
	v_mov_b32_e32 v108, v2
	v_mov_b32_e32 v109, v2
	v_mov_b32_e32 v110, v2
	v_mov_b32_e32 v111, v2
	v_mov_b32_e32 v112, v2
	v_mov_b32_e32 v113, v2
